# MLA main loop: LDS-DMA source addresses from scalar bases (SALU adds + saddr form, constant per-lane offsets) instead of 18 per-lane 64-bit VALU adds per 4 tiles
# speedup vs baseline: 1.0052x; 1.0025x over previous
.LBB0_1187:
	s_mul_hi_i32 s15, s63, 0xc0000
	s_mul_i32 s14, s63, 0xc0000
	v_lshl_add_u64 v[180:181], v[146:147], 0, s[14:15]
	v_lshl_add_u64 v[182:183], v[162:163], 0, s[14:15]
	s_lshl_b64 s[14:15], s[48:49], 13
	v_lshl_add_u64 v[16:17], v[16:17], 0, s[14:15]
	v_lshl_add_u64 v[184:185], v[164:165], 0, v[16:17]
	v_readfirstlane_b32 s77, v180
	v_readfirstlane_b32 s83, v181
	v_readfirstlane_b32 s32, v184
	v_readfirstlane_b32 s85, v185
	v_mov_b32_e32 v115, 0
	s_nop 1
	s_sub_u32 s32, s32, 0x80
	s_subb_u32 s85, s85, 0
	v_subrev_u32_e32 v112, s77, v180
	v_subrev_u32_e32 v114, s77, v182
	v_subrev_u32_e32 v113, s32, v184
	s_nop 0
	s_add_u32 s77, s77, s10
	s_addc_u32 s83, s83, s11
	s_add_u32 s32, s32, s10
	s_addc_u32 s85, s85, s11
	v_mov_b64_e32 v[30:31], v[14:15]
	v_mov_b64_e32 v[46:47], v[14:15]
	s_mov_b32 s13, -4
	v_mov_b64_e32 v[28:29], v[12:13]
	v_mov_b64_e32 v[26:27], v[10:11]
	v_mov_b64_e32 v[24:25], v[8:9]
	v_mov_b64_e32 v[22:23], v[6:7]
	v_mov_b64_e32 v[20:21], v[4:5]
	v_mov_b64_e32 v[18:19], v[2:3]
	v_mov_b64_e32 v[16:17], v[0:1]
	v_mov_b64_e32 v[44:45], v[12:13]
	v_mov_b64_e32 v[42:43], v[10:11]
	v_mov_b64_e32 v[40:41], v[8:9]
	v_mov_b64_e32 v[38:39], v[6:7]
	v_mov_b64_e32 v[36:37], v[4:5]
	v_mov_b64_e32 v[34:35], v[2:3]
	v_mov_b64_e32 v[32:33], v[0:1]
	s_mov_b32 s49, s65
	s_barrier
	s_branch .LBB0_1189

.Lmla_early_skip1:
	v_add_u32_e32 v173, s67, v173
	v_add_u32_e32 v197, s67, v197
	v_add_u32_e32 v193, s67, v193
	v_add_u32_e32 v195, s67, v195
	v_add_u32_e32 v192, s67, v192
	v_add_u32_e32 v198, s67, v198
	v_add_u32_e32 v194, s67, v194
	v_add_u32_e32 v196, s67, v196
	s_sub_i32 s67, 0, s67
	s_xor_b32 s66, s66, 0x8000
	s_add_u32 s77, s77, 0xc000
	s_addc_u32 s83, s83, 0
	s_add_u32 s32, s32, 0x200
	s_addc_u32 s85, s85, 0
	s_add_i32 s13, s13, 4
	s_add_i32 s12, s12, 4
	s_cmp_gt_u32 s13, 55
	s_cbranch_scc1 .LBB0_1209
	.p2alignl 6, 3212836864
.LBB0_1189:
	s_add_u32 s98, s77, 0xf609000
	s_addc_u32 s99, s83, 0
	s_mov_b32 m0, s57
	s_and_b64 vcc, exec, s[8:9]
	global_load_lds_dwordx4 v112, s[98:99]
	s_cbranch_vccnz .LBB0_1191
	s_add_i32 m0, s53, 0x9000
	s_nop 0
	global_load_lds_dwordx4 v114, s[98:99]
.LBB0_1191:
	s_add_i32 s16, s42, 0
	s_add_u32 s98, s32, 0x3600100
	s_addc_u32 s99, s85, 0
	s_add_i32 s18, s16, 0x10000
	s_add_i32 m0, s18, s66
	s_add_u32 s100, s77, 0xf60c000
	s_addc_u32 s101, s83, 0
	global_load_lds_dwordx4 v113, s[98:99]
	s_mov_b32 m0, s16
	s_and_b64 vcc, exec, s[8:9]
	global_load_lds_dwordx4 v112, s[100:101]
	s_cbranch_vccnz .LBB0_1193
	s_mov_b32 m0, s53
	s_nop 0
	global_load_lds_dwordx4 v114, s[100:101]
.LBB0_1193:
	s_add_u32 s98, s32, 0x3600180
	s_addc_u32 s99, s85, 0
	s_add_i32 s17, s16, 0x12000
	s_add_i32 m0, s17, s66
	v_exp_f32_e32 v150, v64
	global_load_lds_dwordx4 v113, s[98:99]
	ds_read_b128 v[80:83], v199 offset:12288
	ds_read_b128 v[84:87], v199 offset:18432
	ds_read_b128 v[154:157], v200 offset:12288
	ds_read_b128 v[202:205], v200 offset:18432
	ds_read_b128 v[212:215], v199 offset:12352
	ds_read_b128 v[220:223], v199 offset:18496
	ds_read_b128 v[224:227], v200 offset:12352
	ds_read_b128 v[228:231], v200 offset:18496
	ds_read_b128 v[232:235], v199 offset:12416
	ds_read_b128 v[236:239], v199 offset:18560
	ds_read_b128 v[240:243], v200 offset:12416
	ds_read_b128 v[244:247], v200 offset:18560
	s_waitcnt lgkmcnt(0)
	v_mfma_f32_32x32x16_bf16 v[96:111], v[80:83], v[136:139], 0
	v_exp_f32_e32 v151, v65
	v_exp_f32_e32 v152, v48
	v_exp_f32_e32 v153, v49
	v_exp_f32_e32 v167, v50
	v_exp_f32_e32 v169, v51
	v_exp_f32_e32 v201, v69
	v_exp_f32_e32 v208, v52
	v_mfma_f32_32x32x16_bf16 v[80:95], v[84:87], v[136:139], 0
	v_exp_f32_e32 v209, v55
	v_exp_f32_e32 v219, v74
	v_mfma_f32_32x32x16_bf16 v[96:111], v[154:157], v[132:135], v[96:111]
	v_exp_f32_e32 v155, v66
	v_exp_f32_e32 v156, v67
	v_exp_f32_e32 v157, v68
	v_mfma_f32_32x32x16_bf16 v[96:111], v[212:215], v[128:131], v[96:111]
	v_exp_f32_e32 v212, v72
	v_exp_f32_e32 v213, v73
	v_exp_f32_e32 v214, v56
	v_exp_f32_e32 v215, v57
	v_mfma_f32_32x32x16_bf16 v[96:111], v[224:227], v[124:127], v[96:111]
	v_exp_f32_e32 v224, v77
	v_exp_f32_e32 v225, v60
	v_exp_f32_e32 v226, v61
	v_exp_f32_e32 v227, v78
	v_mfma_f32_32x32x16_bf16 v[96:111], v[232:235], v[120:123], v[96:111]
	v_mfma_f32_32x32x16_bf16 v[96:111], v[240:243], v[116:119], v[96:111]
	v_mfma_f32_32x32x16_bf16 v[80:95], v[202:205], v[132:135], v[80:95]
	v_exp_f32_e32 v202, v53
	v_exp_f32_e32 v203, v70
	v_exp_f32_e32 v204, v71
	v_exp_f32_e32 v205, v54
	v_mfma_f32_32x32x16_bf16 v[80:95], v[220:223], v[128:131], v[80:95]
	v_exp_f32_e32 v220, v75
	v_exp_f32_e32 v221, v58
	v_exp_f32_e32 v222, v59
	v_exp_f32_e32 v223, v76
	v_mfma_f32_32x32x16_bf16 v[80:95], v[228:231], v[124:127], v[80:95]
	v_exp_f32_e32 v228, v79
	v_exp_f32_e32 v229, v62
	v_exp_f32_e32 v230, v63
	v_mfma_f32_32x32x16_bf16 v[80:95], v[236:239], v[120:123], v[80:95]
	ds_read_b128 v[48:51], v173 offset:49152
	ds_read_b128 v[52:55], v173 offset:53248
	ds_read_b128 v[56:59], v197 offset:49152
	ds_read_b128 v[60:63], v197 offset:53248
	ds_read_b128 v[64:67], v193 offset:49152
	ds_read_b128 v[68:71], v193 offset:53248
	ds_read_b128 v[72:75], v195 offset:49152
	ds_read_b128 v[76:79], v195 offset:53248
	v_add_f32_e32 v32, v32, v150
	v_add_f32_e32 v33, v33, v151
	v_cvt_pk_bf16_f32 v154, v150, v151
	v_add_f32_e32 v34, v34, v155
	v_add_f32_e32 v35, v35, v156
	v_cvt_pk_bf16_f32 v155, v155, v156
	v_add_f32_e32 v32, v32, v157
	v_add_f32_e32 v33, v33, v201
	v_cvt_pk_bf16_f32 v156, v157, v201
	v_add_f32_e32 v34, v34, v203
	v_add_f32_e32 v35, v35, v204
	v_cvt_pk_bf16_f32 v157, v203, v204
	v_mfma_f32_32x32x16_bf16 v[80:95], v[244:247], v[116:119], v[80:95]
	s_and_b64 vcc, exec, s[6:7]
	s_waitcnt lgkmcnt(0)
	v_mfma_f32_32x32x16_bf16 v[16:31], v[52:55], v[154:157], v[16:31]
	v_mfma_f32_32x32x16_bf16 v[0:15], v[48:51], v[154:157], v[0:15]
	v_add_f32_e32 v32, v32, v212
	v_add_f32_e32 v33, v33, v213
	v_cvt_pk_bf16_f32 v48, v212, v213
	v_add_f32_e32 v34, v34, v219
	v_add_f32_e32 v35, v35, v220
	v_cvt_pk_bf16_f32 v49, v219, v220
	v_add_f32_e32 v32, v32, v223
	v_add_f32_e32 v33, v33, v224
	v_cvt_pk_bf16_f32 v50, v223, v224
	v_cvt_pk_bf16_f32 v51, v227, v228
	v_add_f32_e32 v34, v34, v227
	v_add_f32_e32 v35, v35, v228
	v_mfma_f32_32x32x16_bf16 v[16:31], v[60:63], v[48:51], v[16:31]
	v_mfma_f32_32x32x16_bf16 v[0:15], v[56:59], v[48:51], v[0:15]
	v_add_f32_e32 v32, v32, v152
	v_add_f32_e32 v33, v33, v153
	v_cvt_pk_bf16_f32 v52, v152, v153
	v_add_f32_e32 v34, v34, v167
	v_add_f32_e32 v35, v35, v169
	v_cvt_pk_bf16_f32 v53, v167, v169
	v_add_f32_e32 v32, v32, v208
	v_add_f32_e32 v33, v33, v202
	v_cvt_pk_bf16_f32 v54, v208, v202
	v_cvt_pk_bf16_f32 v55, v205, v209
	v_add_f32_e32 v34, v34, v205
	v_add_f32_e32 v35, v35, v209
	v_mfma_f32_32x32x16_bf16 v[16:31], v[68:71], v[52:55], v[16:31]
	v_mfma_f32_32x32x16_bf16 v[0:15], v[64:67], v[52:55], v[0:15]
	v_add_f32_e32 v32, v32, v214
	v_add_f32_e32 v33, v33, v215
	v_cvt_pk_bf16_f32 v48, v214, v215
	v_add_f32_e32 v34, v34, v221
	v_add_f32_e32 v35, v35, v222
	v_cvt_pk_bf16_f32 v49, v221, v222
	v_add_f32_e32 v32, v32, v225
	v_add_f32_e32 v33, v33, v226
	v_cvt_pk_bf16_f32 v50, v225, v226
	v_cvt_pk_bf16_f32 v51, v229, v230
	v_add_f32_e32 v34, v34, v229
	v_add_f32_e32 v35, v35, v230
	v_mfma_f32_32x32x16_bf16 v[16:31], v[76:79], v[48:51], v[16:31]
	v_mfma_f32_32x32x16_bf16 v[0:15], v[72:75], v[48:51], v[0:15]
	s_cbranch_vccz .Lmla_nf_0

.Lmla_early_skip0:
	s_add_u32 s98, s77, 0xf60f000
	s_addc_u32 s99, s83, 0
	s_add_i32 m0, s52, 0x3000
	s_add_u32 s100, s32, 0x3600200
	s_addc_u32 s101, s85, 0
	global_load_lds_dwordx4 v112, s[98:99]
	s_mov_b64 s[14:15], -1
	s_and_b64 vcc, exec, s[38:39]
	s_cbranch_vccz .LBB0_1201
	s_sub_i32 m0, s60, s66
	s_add_i32 m0, m0, 0x8000
	s_mul_i32 s48, s12, 0x3000
	global_load_lds_dwordx4 v113, s[100:101]
	v_lshl_add_u64 v[82:83], v[176:177], 0, s[48:49]
	v_lshl_add_u64 v[82:83], v[82:83], 0, s[42:43]
	s_mov_b64 s[14:15], 0x12000
	v_lshl_add_u64 v[82:83], v[82:83], 0, s[14:15]
	s_mov_b64 s[14:15], 0
.LBB0_1201:
	s_andn2_b64 vcc, exec, s[14:15]
	s_mov_b32 s14, s54
	s_cbranch_vccnz .LBB0_1203
	s_add_i32 m0, s53, 0x3000
	s_nop 0
	global_load_lds_dwordx4 v114, s[98:99]
	s_sub_i32 m0, s60, s66
	s_add_i32 m0, m0, 0x8000
	s_add_u32 s98, s77, 0xf612000
	s_addc_u32 s99, s83, 0
	global_load_lds_dwordx4 v113, s[100:101]
	v_lshl_add_u64 v[82:83], s[98:99], 0, v[114:115]
	s_add_i32 m0, s52, 0x6000
	s_mov_b32 s14, s55
	global_load_lds_dwordx4 v112, s[98:99]
.LBB0_1203:
	s_mov_b32 m0, s14
	s_add_u32 s98, s32, 0x3600280
	s_addc_u32 s99, s85, 0
	global_load_lds_dwordx4 v[82:83], off
	s_sub_i32 m0, s62, s66
	s_add_i32 m0, m0, 0x8000
	v_exp_f32_e32 v150, v64
	global_load_lds_dwordx4 v113, s[98:99]
	ds_read_b128 v[80:83], v199 offset:36864
	ds_read_b128 v[84:87], v199 offset:43008
	ds_read_b128 v[154:157], v200 offset:36864
	ds_read_b128 v[186:189], v200 offset:43008
	ds_read_b128 v[202:205], v199 offset:36928
	ds_read_b128 v[212:215], v199 offset:43072
	ds_read_b128 v[220:223], v200 offset:36928
	ds_read_b128 v[224:227], v200 offset:43072
	ds_read_b128 v[228:231], v199 offset:36992
	ds_read_b128 v[232:235], v199 offset:43136
	ds_read_b128 v[236:239], v200 offset:36992
	ds_read_b128 v[240:243], v200 offset:43136
	s_waitcnt lgkmcnt(0)
	v_mfma_f32_32x32x16_bf16 v[96:111], v[80:83], v[136:139], 0
	v_exp_f32_e32 v151, v65
	v_exp_f32_e32 v152, v48
	v_exp_f32_e32 v153, v49
	v_exp_f32_e32 v167, v50
	v_exp_f32_e32 v169, v51
	v_exp_f32_e32 v190, v69
	v_exp_f32_e32 v191, v52
	v_mfma_f32_32x32x16_bf16 v[80:95], v[84:87], v[136:139], 0
	v_exp_f32_e32 v201, v55
	v_exp_f32_e32 v208, v74
	v_exp_f32_e32 v209, v75
	v_exp_f32_e32 v219, v60
	v_mfma_f32_32x32x16_bf16 v[96:111], v[154:157], v[132:135], v[96:111]
	v_exp_f32_e32 v155, v66
	v_exp_f32_e32 v156, v67
	v_exp_f32_e32 v157, v68
	v_mfma_f32_32x32x16_bf16 v[96:111], v[202:205], v[128:131], v[96:111]
	v_exp_f32_e32 v202, v72
	v_exp_f32_e32 v203, v73
	v_exp_f32_e32 v204, v56
	v_exp_f32_e32 v205, v57
	v_mfma_f32_32x32x16_bf16 v[96:111], v[220:223], v[124:127], v[96:111]
	v_exp_f32_e32 v220, v61
	v_exp_f32_e32 v221, v78
	v_exp_f32_e32 v222, v79
	v_exp_f32_e32 v223, v62
	v_mfma_f32_32x32x16_bf16 v[96:111], v[228:231], v[120:123], v[96:111]
	v_mfma_f32_32x32x16_bf16 v[96:111], v[236:239], v[116:119], v[96:111]
	v_mfma_f32_32x32x16_bf16 v[80:95], v[186:189], v[132:135], v[80:95]
	v_exp_f32_e32 v186, v53
	v_exp_f32_e32 v187, v70
	v_exp_f32_e32 v188, v71
	v_exp_f32_e32 v189, v54
	v_mfma_f32_32x32x16_bf16 v[80:95], v[212:215], v[128:131], v[80:95]
	v_exp_f32_e32 v212, v58
	v_exp_f32_e32 v213, v59
	v_exp_f32_e32 v214, v76
	v_exp_f32_e32 v215, v77
	v_mfma_f32_32x32x16_bf16 v[80:95], v[224:227], v[124:127], v[80:95]
	v_exp_f32_e32 v224, v63
	v_mfma_f32_32x32x16_bf16 v[80:95], v[232:235], v[120:123], v[80:95]
	ds_read_b128 v[48:51], v192 offset:16384
	ds_read_b128 v[52:55], v192 offset:20480
	ds_read_b128 v[56:59], v198 offset:16384
	ds_read_b128 v[60:63], v198 offset:20480
	ds_read_b128 v[64:67], v194 offset:16384
	ds_read_b128 v[68:71], v194 offset:20480
	ds_read_b128 v[72:75], v196 offset:16384
	ds_read_b128 v[76:79], v196 offset:20480
	v_add_f32_e32 v32, v32, v150
	v_add_f32_e32 v33, v33, v151
	v_cvt_pk_bf16_f32 v154, v150, v151
	v_add_f32_e32 v34, v34, v155
	v_add_f32_e32 v35, v35, v156
	v_cvt_pk_bf16_f32 v155, v155, v156
	v_add_f32_e32 v32, v32, v157
	v_add_f32_e32 v33, v33, v190
	v_cvt_pk_bf16_f32 v156, v157, v190
	v_add_f32_e32 v34, v34, v187
	v_add_f32_e32 v35, v35, v188
	v_cvt_pk_bf16_f32 v157, v187, v188
	v_mfma_f32_32x32x16_bf16 v[80:95], v[240:243], v[116:119], v[80:95]
	s_and_b64 vcc, exec, s[6:7]
	s_waitcnt lgkmcnt(0)
	v_mfma_f32_32x32x16_bf16 v[16:31], v[52:55], v[154:157], v[16:31]
	v_mfma_f32_32x32x16_bf16 v[0:15], v[48:51], v[154:157], v[0:15]
	v_add_f32_e32 v32, v32, v202
	v_add_f32_e32 v33, v33, v203
	v_cvt_pk_bf16_f32 v48, v202, v203
	v_add_f32_e32 v34, v34, v208
	v_add_f32_e32 v35, v35, v209
	v_cvt_pk_bf16_f32 v49, v208, v209
	v_add_f32_e32 v32, v32, v214
	v_add_f32_e32 v33, v33, v215
	v_cvt_pk_bf16_f32 v50, v214, v215
	v_cvt_pk_bf16_f32 v51, v221, v222
	v_add_f32_e32 v34, v34, v221
	v_add_f32_e32 v35, v35, v222
	v_mfma_f32_32x32x16_bf16 v[16:31], v[60:63], v[48:51], v[16:31]
	v_mfma_f32_32x32x16_bf16 v[0:15], v[56:59], v[48:51], v[0:15]
	v_add_f32_e32 v32, v32, v152
	v_add_f32_e32 v33, v33, v153
	v_cvt_pk_bf16_f32 v52, v152, v153
	v_add_f32_e32 v34, v34, v167
	v_add_f32_e32 v35, v35, v169
	v_cvt_pk_bf16_f32 v53, v167, v169
	v_add_f32_e32 v32, v32, v191
	v_add_f32_e32 v33, v33, v186
	v_cvt_pk_bf16_f32 v54, v191, v186
	v_cvt_pk_bf16_f32 v55, v189, v201
	v_add_f32_e32 v34, v34, v189
	v_add_f32_e32 v35, v35, v201
	v_mfma_f32_32x32x16_bf16 v[16:31], v[68:71], v[52:55], v[16:31]
	v_mfma_f32_32x32x16_bf16 v[0:15], v[64:67], v[52:55], v[0:15]
	v_add_f32_e32 v32, v32, v204
	v_add_f32_e32 v33, v33, v205
	v_cvt_pk_bf16_f32 v48, v204, v205
	v_add_f32_e32 v34, v34, v212
	v_add_f32_e32 v35, v35, v213
	v_cvt_pk_bf16_f32 v49, v212, v213
	v_add_f32_e32 v32, v32, v219
	v_add_f32_e32 v33, v33, v220
	v_cvt_pk_bf16_f32 v50, v219, v220
	v_cvt_pk_bf16_f32 v51, v223, v224
	v_add_f32_e32 v34, v34, v223
	v_add_f32_e32 v35, v35, v224
	v_mfma_f32_32x32x16_bf16 v[16:31], v[76:79], v[48:51], v[16:31]
	v_mfma_f32_32x32x16_bf16 v[0:15], v[72:75], v[48:51], v[0:15]
	s_cbranch_vccz .Lmla_nf_2
